# GEMM phase prologues (P1,P5,P7,P8): K-tile 1 LDS-DMAs issued before the first prologue wait (vmcnt 2 -> 8) so both cold K-tiles load concurrently
# baseline (speedup 1.0000x reference)
.LBB0_314:
	s_and_b32 s54, s40, 3
	s_mov_b64 s[40:41], 0x80
	s_add_i32 m0, s76, 0x18000
	v_lshl_add_u64 v[6:7], v[6:7], 0, s[40:41]
	s_lshl_b32 s55, s1, 13
	s_lshl_b32 s61, s54, 12
	global_load_lds_dwordx4 v[6:7], off
	v_lshl_add_u64 v[4:5], v[4:5], 0, s[40:41]
	s_add_i32 m0, s76, 0x1a000
	s_add_i32 s80, s76, 0x8000
	s_add_i32 s81, s76, 0xa000
	global_load_lds_dwordx4 v[4:5], off
	v_lshl_add_u64 v[0:1], v[0:1], 0, s[40:41]
	s_mov_b32 m0, s80
	s_add_u32 s62, s70, 0x80080
	global_load_lds_dwordx4 v[0:1], off
	v_lshl_add_u64 v[0:1], v[2:3], 0, s[40:41]
	s_mov_b32 m0, s81
	s_addc_u32 s63, s71, 0
	global_load_lds_dwordx4 v[0:1], off
	s_add_i32 m0, s76, 0x1c000
	v_lshl_add_u64 v[0:1], s[62:63], 0, v[146:147]
	global_load_lds_dwordx4 v[0:1], off
	v_lshl_add_u64 v[0:1], s[62:63], 0, v[142:143]
	s_add_i32 m0, s76, 0x1e000
	s_sext_i32_i16 s95, s0
	global_load_lds_dwordx4 v[0:1], off
	v_and_b32_e32 v0, 15, v208
	v_lshlrev_b32_e32 v1, 1, v140
	v_lshl_or_b32 v141, s1, 6, v0
	v_lshl_or_b32 v2, v0, 6, v1
	v_lshlrev_b32_e32 v0, 2, v0
	v_and_b32_e32 v3, 32, v0
	v_bitop3_b32 v2, v2, s55, v3 bitop3:0xde
	v_lshlrev_b32_e32 v3, 6, v208
	s_movk_i32 s0, 0x3c0
	v_and_or_b32 v1, v3, s0, v1
	v_lshlrev_b32_e32 v3, 2, v208
	v_and_b32_e32 v3, 32, v3
	v_bitop3_b32 v178, s61, v1, v3 bitop3:0xf6
	s_cmpk_lt_u32 s60, 0x100
	v_lshlrev_b32_e32 v1, 9, v208
	s_cselect_b64 s[60:61], -1, 0
	s_lshl_b32 s1, s1, 8
	v_and_b32_e32 v1, 0x70000, v1
	v_lshlrev_b32_e32 v3, 12, v11
	s_add_i32 s1, s1, 0
	v_or3_b32 v1, v9, v1, v3
	s_add_i32 s1, s1, 0x20000
	v_add_u32_e32 v154, v1, v10
	v_lshlrev_b32_e32 v1, 5, v8
	s_waitcnt vmcnt(8)
	s_barrier
	s_waitcnt vmcnt(6)
	v_add_u32_e32 v179, s1, v0
	v_lshl_or_b32 v0, s54, 5, v140
	v_and_b32_e32 v1, 0xf0000, v1
	v_lshlrev_b32_e32 v150, 3, v140
	s_lshl_b32 s0, s54, 6
	v_or3_b32 v1, v9, v1, v3
	s_add_i32 s82, 0, 0x10000
	s_add_i32 s83, 0, 0x14000
	v_lshlrev_b32_e32 v185, 1, v0
	v_mbcnt_lo_u32_b32 v0, -1, 0
	v_lshl_add_u64 v[152:153], s[58:59], 0, v[150:151]
	v_mov_b32_e32 v155, v151
	v_add_u32_e32 v156, v1, v10
	v_mov_b32_e32 v157, v151
	v_mov_b64_e32 v[158:159], 0x300
	v_mov_b64_e32 v[160:161], 0x2ff
	v_add_u32_e32 v180, s82, v178
	v_add_u32_e32 v181, s83, v178
	v_add_u32_e32 v182, 0, v2
	s_mov_b32 s84, 0x40000
	s_mov_b32 s85, 0x48000
	s_mov_b32 s90, 0x50000
	s_lshl_b32 s91, s0, 1
	v_mov_b32_e32 v183, 0x358637bd
	s_mov_b32 s92, 0xf800000
	v_mov_b32_e32 v184, 0x260
	v_mov_b32_e32 v186, 0x3e38aa3b
	v_mbcnt_hi_u32_b32 v187, -1, v0
	s_mov_b32 s93, 0
	s_barrier
	s_branch .LBB0_317

.LBB0_535:
	s_mov_b64 s[38:39], 0x80
	s_and_b32 s64, s1, 3
	s_add_i32 m0, s60, 0x18000
	v_lshl_add_u64 v[6:7], v[6:7], 0, s[38:39]
	s_lshl_b32 s1, s0, 13
	s_lshl_b32 s41, s64, 12
	global_load_lds_dwordx4 v[6:7], off
	v_lshl_add_u64 v[4:5], v[4:5], 0, s[38:39]
	s_add_i32 m0, s60, 0x1a000
	s_add_i32 s65, s60, 0x8000
	s_add_i32 s66, s60, 0xa000
	global_load_lds_dwordx4 v[4:5], off
	v_lshl_add_u64 v[0:1], v[0:1], 0, s[38:39]
	s_mov_b32 m0, s65
	s_add_u32 s4, s56, 0x80080
	global_load_lds_dwordx4 v[0:1], off
	v_lshl_add_u64 v[0:1], v[2:3], 0, s[38:39]
	s_mov_b32 m0, s66
	s_addc_u32 s5, s57, 0
	global_load_lds_dwordx4 v[0:1], off
	s_add_i32 m0, s60, 0x1c000
	v_lshl_add_u64 v[0:1], s[4:5], 0, v[128:129]
	global_load_lds_dwordx4 v[0:1], off
	v_lshl_add_u64 v[0:1], s[4:5], 0, v[130:131]
	s_add_i32 m0, s60, 0x1e000
	v_lshlrev_b32_e32 v3, 2, v208
	global_load_lds_dwordx4 v[0:1], off
	v_and_b32_e32 v0, 15, v208
	v_bfe_u32 v1, v208, 4, 2
	v_lshl_or_b32 v144, s0, 6, v0
	v_lshlrev_b32_e32 v2, 4, v1
	v_lshlrev_b32_e32 v4, 6, v208
	s_movk_i32 s0, 0x3c0
	v_lshl_or_b32 v0, v0, 6, v2
	v_and_b32_e32 v3, 32, v3
	v_and_or_b32 v2, v4, s0, v2
	v_bitop3_b32 v0, v0, s1, v3 bitop3:0xde
	v_bitop3_b32 v145, s41, v2, v3 bitop3:0xf6
	v_lshlrev_b32_e32 v2, 2, v1
	v_cmp_eq_u32_e64 s[0:1], 0, v1
	v_lshlrev_b32_e32 v1, 9, v208
	v_lshl_or_b32 v146, s64, 5, v2
	v_and_b32_e32 v1, 0x70000, v1
	v_lshlrev_b32_e32 v2, 12, v10
	v_or3_b32 v1, v8, v1, v2
	v_add_u32_e32 v132, v1, v9
	v_lshlrev_b32_e32 v1, 5, v11
	s_waitcnt vmcnt(8)
	s_barrier
	s_waitcnt vmcnt(6)
	s_cmpk_lt_u32 s40, 0x100
	v_and_b32_e32 v1, 0xf0000, v1
	s_cselect_b64 s[40:41], -1, 0
	v_or3_b32 v1, v8, v1, v2
	s_add_i32 s70, 0, 0x10000
	s_add_i32 s71, 0, 0x14000
	v_add_u32_e32 v149, 0, v0
	v_mbcnt_lo_u32_b32 v0, -1, 0
	s_ashr_i32 s67, s30, 31
	s_mov_b32 s68, s30
	s_ashr_i32 s69, s2, 31
	v_mov_b32_e32 v133, v129
	v_add_u32_e32 v134, v1, v9
	v_mov_b32_e32 v135, v129
	v_mov_b64_e32 v[136:137], 0x100
	v_mov_b64_e32 v[138:139], 0xff
	v_add_u32_e32 v147, s70, v145
	v_add_u32_e32 v148, s71, v145
	v_mbcnt_hi_u32_b32 v150, -1, v0
	s_mov_b32 s72, 0
	s_barrier
	s_branch .LBB0_538

.LBB0_633:
	s_lshl_b32 s6, s6, 5
	s_and_b32 s36, s6, 0x60
	s_mov_b64 s[6:7], 0x80
	s_add_i32 m0, s43, 0x18000
	v_lshl_add_u64 v[6:7], v[6:7], 0, s[6:7]
	s_lshl_b32 s19, s1, 13
	s_lshl_b32 s37, s36, 7
	global_load_lds_dwordx4 v[6:7], off
	v_lshl_add_u64 v[4:5], v[4:5], 0, s[6:7]
	s_add_i32 m0, s43, 0x1a000
	s_add_i32 s58, s43, 0x8000
	s_add_i32 s59, s43, 0xa000
	global_load_lds_dwordx4 v[4:5], off
	v_lshl_add_u64 v[0:1], v[0:1], 0, s[6:7]
	s_mov_b32 m0, s58
	s_add_u32 s20, s46, 0x80080
	global_load_lds_dwordx4 v[0:1], off
	v_lshl_add_u64 v[0:1], v[2:3], 0, s[6:7]
	s_mov_b32 m0, s59
	s_addc_u32 s21, s47, 0
	global_load_lds_dwordx4 v[0:1], off
	s_add_i32 m0, s43, 0x1c000
	v_lshl_add_u64 v[0:1], s[20:21], 0, v[132:133]
	global_load_lds_dwordx4 v[0:1], off
	v_lshl_add_u64 v[0:1], s[20:21], 0, v[128:129]
	s_add_i32 m0, s43, 0x1e000
	s_sext_i32_i16 s66, s0
	global_load_lds_dwordx4 v[0:1], off
	v_and_b32_e32 v0, 15, v208
	v_lshlrev_b32_e32 v1, 1, v11
	v_lshl_or_b32 v148, s1, 6, v0
	v_lshl_or_b32 v2, v0, 6, v1
	v_lshlrev_b32_e32 v0, 2, v0
	v_and_b32_e32 v3, 32, v0
	v_bitop3_b32 v2, v2, s19, v3 bitop3:0xde
	v_lshlrev_b32_e32 v3, 6, v208
	s_movk_i32 s0, 0x3c0
	s_cmpk_lt_u32 s18, 0x100
	v_and_or_b32 v1, v3, s0, v1
	s_cselect_b64 s[18:19], -1, 0
	s_lshl_b32 s0, s1, 8
	s_add_i32 s0, s0, 0
	v_lshlrev_b32_e32 v3, 2, v208
	s_add_i32 s0, s0, 0x20000
	v_and_b32_e32 v3, 32, v3
	v_add_u32_e32 v151, s0, v0
	v_lshlrev_b32_e32 v0, 9, v208
	v_bitop3_b32 v149, s37, v1, v3 bitop3:0xf6
	v_and_b32_e32 v0, 0x70000, v0
	v_lshlrev_b32_e32 v1, 12, v12
	v_or3_b32 v0, v9, v0, v1
	v_add_u32_e32 v136, v0, v10
	v_lshlrev_b32_e32 v0, 5, v8
	s_waitcnt vmcnt(8)
	s_barrier
	s_waitcnt vmcnt(6)
	v_and_b32_e32 v0, 0xf0000, v0
	v_or3_b32 v0, v9, v0, v1
	s_add_i32 s60, 0, 0x10000
	s_add_i32 s61, 0, 0x14000
	v_or_b32_e32 v150, s36, v11
	v_mov_b32_e32 v137, v133
	v_add_u32_e32 v138, v0, v10
	v_mov_b32_e32 v139, v133
	v_mov_b64_e32 v[140:141], 0x580
	v_mov_b64_e32 v[142:143], 0x57f
	v_add_u32_e32 v152, s60, v149
	v_add_u32_e32 v153, s61, v149
	v_add_u32_e32 v154, 0, v2
	s_movk_i32 s62, 0x2c00
	s_mov_b32 s63, 0
	s_barrier
	s_branch .LBB0_636

.LBB0_713:
	s_lshl_b32 s5, s5, 5
	s_mov_b64 s[18:19], 0x80
	s_and_b32 s5, s5, 0x60
	s_add_i32 m0, s33, 0x18000
	v_lshl_add_u64 v[6:7], v[6:7], 0, s[18:19]
	s_lshl_b32 s22, s0, 13
	s_lshl_b32 s23, s5, 7
	global_load_lds_dwordx4 v[6:7], off
	v_lshl_add_u64 v[4:5], v[4:5], 0, s[18:19]
	s_add_i32 m0, s33, 0x1a000
	s_add_i32 s40, s33, 0x8000
	s_add_i32 s41, s33, 0xa000
	global_load_lds_dwordx4 v[4:5], off
	v_lshl_add_u64 v[0:1], v[0:1], 0, s[18:19]
	s_mov_b32 m0, s40
	s_add_u32 s20, s28, 0x160080
	global_load_lds_dwordx4 v[0:1], off
	v_lshl_add_u64 v[0:1], v[2:3], 0, s[18:19]
	s_mov_b32 m0, s41
	s_addc_u32 s21, s29, 0
	global_load_lds_dwordx4 v[0:1], off
	s_add_i32 m0, s33, 0x1c000
	v_lshl_add_u64 v[0:1], s[20:21], 0, v[128:129]
	global_load_lds_dwordx4 v[0:1], off
	v_lshl_add_u64 v[0:1], s[20:21], 0, v[130:131]
	s_add_i32 m0, s33, 0x1e000
	v_lshlrev_b32_e32 v3, 2, v208
	global_load_lds_dwordx4 v[0:1], off
	v_and_b32_e32 v0, 15, v208
	v_bfe_u32 v1, v208, 4, 2
	v_lshl_or_b32 v144, s0, 6, v0
	v_lshlrev_b32_e32 v2, 4, v1
	v_lshlrev_b32_e32 v4, 6, v208
	s_movk_i32 s0, 0x3c0
	v_lshl_or_b32 v0, v0, 6, v2
	v_and_b32_e32 v3, 32, v3
	v_and_or_b32 v2, v4, s0, v2
	s_waitcnt vmcnt(8)
	s_barrier
	s_waitcnt vmcnt(6)
	s_cmpk_lt_u32 s4, 0x100
	v_bitop3_b32 v0, v0, s22, v3 bitop3:0xde
	v_bitop3_b32 v145, s23, v2, v3 bitop3:0xf6
	s_cselect_b64 s[20:21], -1, 0
	s_add_i32 s43, 0, 0x10000
	s_add_i32 s44, 0, 0x14000
	s_sext_i32_i8 s48, s1
	s_ashr_i32 s42, s30, 31
	v_lshl_or_b32 v146, v1, 2, s5
	v_add3_u32 v132, v10, v8, v9
	v_mov_b32_e32 v133, v129
	v_add3_u32 v134, v11, v8, v9
	v_mov_b32_e32 v135, v129
	v_mov_b64_e32 v[136:137], 0x100
	v_mov_b64_e32 v[138:139], 0xff
	v_add_u32_e32 v147, s43, v145
	v_add_u32_e32 v148, s44, v145
	v_add_u32_e32 v149, 0, v0
	s_barrier
	s_branch .LBB0_716
